# plus prep phase: wave-wide sums with DPP and permlane swaps instead of ds_bpermute round trips (same pairing tree)
# speedup vs baseline: 1.0032x; 1.0032x over previous
; __device__ __forceinline__ unsigned cvt_pk_bf16(float lo, float hi) { f32x2_cv v = {lo, hi}; bf16x2_cv b = __builtin_convertvector(v, bf16x2_cv); return __builtin_bit_cast(unsigned, b); }
; __device__ __forceinline__ float bf_lo(unsigned u) { return __uint_as_float(u << 16); }
; __device__ __forceinline__ float bf_hi(unsigned u) { return __uint_as_float(u & 0xffff0000u); }
; __device__ __forceinline__ float wave_sum(float v) {
; #pragma unroll
;     for (int o = 1; o < 64; o <<= 1) v += __shfl_xor(v, o);
;     return v;
; }
; __global__ void __launch_bounds__(NTHR) fwd_kernel(Args args) {
;     ...
;                 { const u32x4 kv = *(const u32x4*)((const bf16*)(ws + WS_Z2) + (size_t)t * 1024 + 512 + 8 * lane); float ss = 0.f;
; #pragma unroll
;                   for (int e = 0; e < 4; ++e) { const float x = bf_lo(kv[e]), y = bf_hi(kv[e]); ss += x * x + y * y; }
;                   ss += __shfl_xor(ss, 1); ss += __shfl_xor(ss, 2);
;                   if (t < SEQ) kmx0 = fmaxf(kmx0, ss); else kmx1 = fmaxf(kmx1, ss); }
;                 { const u32x2 v = ((const u32x2*)zr)[lane]; float x0 = bf_lo(v.x), x1 = bf_hi(v.x), x2 = bf_lo(v.y), x3 = bf_hi(v.y);
;                   const float rs = __builtin_amdgcn_rsqf(wave_sum(x0 * x0 + x1 * x1 + x2 * x2 + x3 * x3) * (1.0f / 256.0f) + 1e-6f); const f32x4 gq = ((const f32x4*)q_norm)[lane];
;                   u32x2 o; o.x = cvt_pk_bf16(x0 * rs * gq.x, x1 * rs * gq.y); o.y = cvt_pk_bf16(x2 * rs * gq.z, x3 * rs * gq.w); ((u32x2*)(CQN + (size_t)t * 256))[lane] = o; }
;                 { const unsigned v = ((const unsigned*)(zr + 256))[lane]; float x0 = bf_lo(v), x1 = bf_hi(v);
;                   const float rs = __builtin_amdgcn_rsqf(wave_sum(x0 * x0 + x1 * x1) * (1.0f / 128.0f) + 1e-6f);
;                   ((unsigned*)(CKVN + (size_t)t * 128))[lane] = cvt_pk_bf16(x0 * rs * kv_norm[2 * lane], x1 * rs * kv_norm[2 * lane + 1]); }
;                 if (lane < 16) { const float x1 = bf_lo((unsigned)zr[384 + lane]), x2 = bf_lo((unsigned)zr[400 + lane]); float s, c; sincos_acc((float)pos[t] * ((const float*)(ws + WS_TAB))[lane], s, c);
;                   KR[(size_t)t * 32 + lane] = (bf16)(cvt_pk_bf16(x1 * c - x2 * s, 0.f) & 0xffffu); KR[(size_t)t * 32 + 16 + lane] = (bf16)(cvt_pk_bf16(x2 * c + x1 * s, 0.f) & 0xffffu); }
.Lpool_pre_skip:
	s_lshl_b64 s[18:19], s[42:43], 9
	s_waitcnt vmcnt(0) lgkmcnt(0)
	v_lshlrev_b32_e32 v31, 16, v27
	v_lshlrev_b32_e32 v30, 16, v26
	v_and_b32_e32 v27, 0xffff0000, v27
	v_and_b32_e32 v26, 0xffff0000, v26
	v_pk_mul_f32 v[26:27], v[26:27], v[26:27]
	s_nop 0
	v_pk_fma_f32 v[26:27], v[30:31], v[30:31], v[26:27]
	v_lshlrev_b32_e32 v31, 16, v29
	v_lshlrev_b32_e32 v30, 16, v28
	v_and_b32_e32 v29, 0xffff0000, v29
	v_and_b32_e32 v28, 0xffff0000, v28
	v_pk_mul_f32 v[28:29], v[28:29], v[28:29]
	v_add_f32_e32 v25, v26, v27
	v_pk_fma_f32 v[28:29], v[30:31], v[30:31], v[28:29]
	s_nop 0
	v_add_f32_e32 v25, v25, v28
	v_add_f32_e32 v25, v25, v29
	s_nop 1
	v_add_f32_dpp v52, v25, v25 quad_perm:[1,0,3,2] row_mask:0xf bank_mask:0xf
	v_mov_b32_e32 v25, v3
	v_lshl_add_u64 v[30:31], s[44:45], 0, v[24:25]
	v_mov_b32_e32 v32, v124
	v_mov_b32_e32 v33, v125
	v_mov_b32_e32 v26, v128
	v_mov_b32_e32 v27, v129
	v_mov_b32_e32 v28, v130
	v_mov_b32_e32 v29, v131
	s_nop 1
	v_mov_b32_dpp v53, v52 quad_perm:[2,3,0,1] row_mask:0xf bank_mask:0xf
	s_waitcnt lgkmcnt(0)
	v_lshlrev_b32_e32 v38, 16, v32
	v_and_b32_e32 v39, 0xffff0000, v32
	v_lshlrev_b32_e32 v34, 16, v33
	v_and_b32_e32 v35, 0xffff0000, v33
	v_pk_mul_f32 v[32:33], v[38:39], v[38:39]
	v_pk_mul_f32 v[36:37], v[34:35], v[34:35]
	v_add_f32_e32 v25, v32, v33
	v_add_f32_e32 v25, v36, v25
	v_add_f32_e32 v25, v37, v25
	s_nop 1
	v_add_f32_dpp v25, v25, v25 quad_perm:[1,0,3,2] row_mask:0xf bank_mask:0xf
	s_nop 1
	v_add_f32_dpp v25, v25, v25 quad_perm:[2,3,0,1] row_mask:0xf bank_mask:0xf
	s_nop 1
	v_mov_b32_dpp v32, v25 row_shl:4 row_mask:0xf bank_mask:0x5
	v_mov_b32_dpp v32, v25 row_shr:4 row_mask:0xf bank_mask:0xa
	v_add_f32_e32 v25, v25, v32
	s_nop 1
	v_add_f32_dpp v25, v25, v25 row_ror:8 row_mask:0xf bank_mask:0xf
	v_mov_b32_e32 v32, v25
	v_mov_b32_e32 v158, v25
	s_nop 1
	v_permlane16_swap_b32_e32 v32, v158
	v_add_f32_e32 v25, v32, v158
	v_mov_b32_e32 v32, v25
	v_mov_b32_e32 v158, v25
	s_nop 1
	v_permlane32_swap_b32_e32 v32, v158
	v_add_f32_e32 v25, v32, v158
	v_fmamk_f32 v25, v25, 0x3b800000, v212
	v_rsq_f32_e32 v32, v25
	s_nop 0
	v_pk_mul_f32 v[36:37], v[32:33], v[38:39] op_sel_hi:[0,1]
	v_pk_mul_f32 v[32:33], v[32:33], v[34:35] op_sel_hi:[0,1]
	v_pk_mul_f32 v[26:27], v[26:27], v[36:37]
	v_pk_mul_f32 v[28:29], v[28:29], v[32:33]
	v_cvt_pk_bf16_f32 v26, v26, v27
	v_cvt_pk_bf16_f32 v27, v28, v29
	v_lshl_add_u64 v[28:29], v[6:7], 0, s[18:19]
	global_store_dwordx2 v[28:29], v[26:27], off
	v_lshl_add_u64 v[26:27], v[30:31], 0, v[18:19]
	v_mov_b32_e32 v25, v126
	s_lshl_b64 s[18:19], s[42:43], 8
	s_waitcnt lgkmcnt(0)
	v_lshlrev_b32_e32 v28, 16, v25
	v_and_b32_e32 v29, 0xffff0000, v25
	v_pk_mul_f32 v[30:31], v[28:29], v[28:29]
	s_nop 0
	v_add_f32_e32 v25, v30, v31
	s_nop 1
	v_add_f32_dpp v25, v25, v25 quad_perm:[1,0,3,2] row_mask:0xf bank_mask:0xf
	s_nop 1
	v_add_f32_dpp v25, v25, v25 quad_perm:[2,3,0,1] row_mask:0xf bank_mask:0xf
	s_nop 1
	v_mov_b32_dpp v30, v25 row_shl:4 row_mask:0xf bank_mask:0x5
	v_mov_b32_dpp v30, v25 row_shr:4 row_mask:0xf bank_mask:0xa
	v_add_f32_e32 v25, v25, v30
	s_nop 1
	v_add_f32_dpp v25, v25, v25 row_ror:8 row_mask:0xf bank_mask:0xf
	v_mov_b32_e32 v30, v25
	v_mov_b32_e32 v158, v25
	s_nop 1
	v_permlane16_swap_b32_e32 v30, v158
	v_add_f32_e32 v25, v30, v158
	v_mov_b32_e32 v30, v25
	v_mov_b32_e32 v158, v25
	s_nop 1
	v_permlane32_swap_b32_e32 v30, v158
	v_add_f32_e32 v25, v30, v158
	v_fmamk_f32 v25, v25, 0x3c000000, v212
	v_rsq_f32_e32 v30, v25
	s_nop 0
	v_pk_mul_f32 v[28:29], v[30:31], v[28:29] op_sel_hi:[0,1]
	v_mov_b32_e32 v30, v132
	v_mov_b32_e32 v31, v133
	v_pk_mul_f32 v[28:29], v[30:31], v[28:29]
	s_nop 0
	v_cvt_pk_bf16_f32 v25, v28, v29
	v_lshl_add_u64 v[28:29], v[10:11], 0, s[18:19]
	global_store_dword v[28:29], v25, off
	s_and_saveexec_b64 s[46:47], s[40:41]
	s_cbranch_execz .LBB0_463
	v_lshl_add_u64 v[26:27], v[26:27], 0, v[20:21]
	v_mov_b32_e32 v25, v134
	s_lshl_b64 s[18:19], s[42:43], 2
	v_mov_b32_e32 v26, v135
	s_add_u32 s18, s36, s18
	s_addc_u32 s19, s37, s19
	v_mov_b32_e32 v27, v136
	s_waitcnt lgkmcnt(0)
	v_lshlrev_b32_e32 v25, 16, v25
	v_lshlrev_b32_e32 v30, 16, v26
	v_mov_b32_e32 v26, v137
	s_mov_b32 s18, 0x6dc9c883
	s_mov_b32 s19, 0x3fc45f30
	v_cvt_f32_i32_e32 v26, v26
	v_mul_f32_e32 v26, v27, v26
	v_cvt_f64_f32_e32 v[26:27], v26
	v_mul_f64 v[28:29], v[26:27], s[18:19]
	v_rndne_f64_e32 v[28:29], v[28:29]
	v_fma_f64 v[26:27], v[26:27], s[18:19], -v[28:29]
	v_cvt_f32_f64_e32 v26, v[26:27]
	v_sin_f32_e32 v28, v26
	v_cos_f32_e32 v29, v26
	s_lshl_b64 s[18:19], s[42:43], 6
	v_mul_f32_e32 v26, v28, v30
	v_fma_f32 v26, v29, v25, -v26
	v_mul_f32_e32 v25, v28, v25
	v_fmac_f32_e32 v25, v29, v30
	v_cvt_pk_bf16_f32 v31, v26, s0
	v_lshl_add_u64 v[26:27], v[14:15], 0, s[18:19]
	v_cvt_pk_bf16_f32 v25, v25, s0
	global_store_short v[26:27], v31, off
	global_store_short v[26:27], v25, off offset:32
